# scans: one static s_setprio 1 for waves 4-7 (backward direction) before the scan loop, s_setprio 0 after it
# baseline (speedup 1.0000x reference)
; #define LAS __attribute__((address_space(3)))
; __device__ __forceinline__ int fresh_lane() { int t; asm volatile("v_mbcnt_lo_u32_b32 %0, -1, 0\n\tv_mbcnt_hi_u32_b32 %0, -1, %0" : "=v"(t)); return t; }
;     constexpr int NT = GDN ? 4 : 5;
;     const int b = bh >> 2, h = bh & 3;
;     const int lane = fresh_lane(), dir = F.wave >> 2, wq = F.wave & 3, lr = lane & 15, lq = lane >> 4;
;     ScanLane L;
;     L.o16 = (unsigned)((wq * 128 + lq * 16 + lr) * 16); L.o8 = (unsigned)((wq * NT * 64 + lq * 16 + lr) * 8); L.o16p = (unsigned)(wq * NT * 512 + (lq * 16 + lr) * 16); L.zq = (unsigned)(((16 * wq + lr) * ZW + 8 * lq) * 2); L.wi = (unsigned)((16 * wq + 4 * lq) * 4);
;     L.pend = (unsigned)(wq * 2048 + (lq * 16 + lr) * 16);   L.gz = (unsigned)(((16 * wq + 4 * lq) * ZW + 4 * lr) * 2); L.mix = (unsigned)(((16 * wq + 4 * lq) * 1024 + 4 * lr) * 2);
;     LAS bf16_t* St = (LAS bf16_t*)F.lds;
;     f32x4 S[NT];
; #pragma unroll
;     for (int t = 0; t < NT; ++t) S[t] = (f32x4){0.f, 0.f, 0.f, 0.f};
;     float* PEND = F.PEND + (GDN ? (size_t)0 : (size_t)1152 * 4096);
;     ScanOps<NT> A0, A1, A2; ScanFin F0, F1;
;     f32x4 Oprev[4];
; #pragma unroll
;     for (int t = 0; t < 4; ++t) { Oprev[t] = (f32x4){0.f, 0.f, 0.f, 0.f}; F0.pend[t] = (v2u){0u, 0u}; F1.pend[t] = (v2u){0u, 0u}; F0.gz[t] = (v2u){0u, 0u}; F1.gz[t] = (v2u){0u, 0u}; }
;     { const int tl = F.wave * 64 + lane; if (tl < 72) ((LAS float*)(St + 4 * 80 * 72))[tl] = (GDN ? F.GLG : F.GLM)[(b * 4 + h) * 72 + tl]; }
;     scan_load<GDN, NT>(F, b, h, dir, L, 0, A0);
;     scan_load<GDN, NT>(F, b, h, dir, L, 1, A1);
.LBB0_345:
	s_or_b64 exec, exec, s[10:11]
	s_cmp_lt_u32 s64, 0x100
	s_cbranch_scc1 .Lprio_m
	s_setprio 1
.Lprio_m:
	v_and_b32_e32 v3, -16, v0
	v_readlane_b32 s0, v251, 36
	v_and_b32_e32 v2, 15, v0
	v_ashrrev_i32_e32 v6, 2, v0
	v_add_u32_e32 v4, s0, v3
	v_readlane_b32 s0, v253, 33
	v_and_b32_e32 v6, -4, v6
	v_readlane_b32 s3, v253, 53
	v_add_u32_e32 v5, s0, v4
	v_or_b32_e32 v5, v5, v2
	v_readlane_b32 s0, v251, 37
	v_lshlrev_b32_e32 v194, 3, v5
	v_readlane_b32 s12, v254, 46
	v_or_b32_e32 v5, s0, v2
	v_add_u32_e32 v7, s0, v6
	v_readlane_b32 s0, v253, 32
	v_readlane_b32 s13, v254, 47
	v_readlane_b32 s8, v251, 60
	v_lshl_add_u32 v195, v0, 4, s0
	v_readlane_b32 s0, v254, 50
	s_waitcnt lgkmcnt(0)
	s_add_u32 s22, s0, 0x3700000
	v_readlane_b32 s0, v254, 51
	s_addc_u32 s23, s0, 0
	v_readlane_b32 s0, v251, 43
	s_add_u32 s0, s16, s0
	s_addc_u32 s1, s17, 0
	s_add_u32 s0, s0, 0x1000
	s_addc_u32 s1, s1, 0
	s_add_u32 s4, s12, s3
	v_readlane_b32 s3, v253, 52
	s_addc_u32 s5, s13, s3
	s_add_u32 s6, s4, 0x2800
	s_addc_u32 s7, s5, 0
	v_readlane_b32 s18, v254, 52
	v_readlane_b32 s9, v251, 61
	v_readlane_b32 s19, v254, 53
	s_add_u32 s8, s18, s8
	s_addc_u32 s9, s19, s9
	v_readlane_b32 s3, v251, 44
	s_add_u32 s3, s16, s3
	s_addc_u32 s11, s17, 0
	s_add_u32 s10, s3, 0x1000
	s_addc_u32 s11, s11, 0
	v_readlane_b32 s3, v252, 63
	s_add_u32 s12, s12, s3
	v_readlane_b32 s3, v252, 62
	v_mad_u32_u24 v196, v5, s66, v3
	s_addc_u32 s13, s13, s3
	v_lshlrev_b32_e32 v120, 2, v7
	s_add_u32 s14, s12, 0x2800
	global_load_dwordx4 v[40:43], v196, s[0:1]
	global_load_dwordx4 v[36:39], v196, s[0:1] offset:64
	s_addc_u32 s15, s13, 0
	global_load_dwordx4 v[92:95], v195, s[6:7] nt
	global_load_dwordx4 v[64:67], v195, s[6:7] offset:1024 nt
	global_load_dwordx4 v[96:99], v195, s[4:5] nt
	global_load_dwordx4 v[68:71], v195, s[4:5] offset:1024 nt
	global_load_dwordx2 v[146:147], v194, s[6:7] offset:2048 nt
	global_load_dwordx2 v[142:143], v194, s[4:5] offset:2048 nt
	global_load_dwordx4 v[60:63], v120, s[8:9]
	global_load_dwordx4 v[24:27], v196, s[10:11]
	global_load_dwordx4 v[20:23], v196, s[10:11] offset:64
	global_load_dwordx4 v[44:47], v195, s[14:15] nt
	global_load_dwordx4 v[28:31], v195, s[14:15] offset:1024 nt
	global_load_dwordx4 v[52:55], v195, s[12:13] nt
	global_load_dwordx4 v[32:35], v195, s[12:13] offset:1024 nt
	global_load_dwordx2 v[140:141], v194, s[14:15] offset:2048 nt
	global_load_dwordx2 v[138:139], v194, s[12:13] offset:2048 nt
	v_readlane_b32 s0, v253, 12
	v_mov_b32_e32 v121, v1
	v_or_b32_e32 v0, v4, v2
	v_subrev_u32_e32 v199, s0, v195
	v_readlane_b32 s0, v251, 62
	v_readlane_b32 s1, v251, 63
	s_add_u32 s0, s18, s0
	s_addc_u32 s1, s19, s1
	v_lshlrev_b32_e32 v4, 3, v2
	v_lshl_add_u64 v[184:185], s[0:1], 0, v[120:121]
	v_readlane_b32 s0, v251, 46
	v_mul_u32_u24_e32 v121, 0x90, v2
	v_mov_b32_e32 v2, v1
	v_lshl_add_u32 v12, v6, 1, s0
	v_readlane_b32 s0, v251, 45
	v_mul_lo_u32 v5, v7, s66
	v_lshlrev_b32_e32 v198, 4, v0
	v_add_u32_e32 v201, s0, v3
	v_mov_b32_e32 v3, v1
	v_mov_b32_e32 v0, v1
	v_mov_b32_e32 v128, v1
	v_mov_b32_e32 v129, v1
	v_mov_b32_e32 v180, 0
	v_mov_b64_e32 v[118:119], v[2:3]
	v_mov_b64_e32 v[114:115], v[2:3]
	v_mov_b64_e32 v[110:111], v[2:3]
	v_mov_b64_e32 v[106:107], v[2:3]
	v_or_b32_e32 v197, v5, v4
	v_lshl_or_b32 v200, v7, 11, v4
	s_mov_b32 s25, 0
	s_mov_b32 s24, -3
	v_mov_b32_e32 v10, 0
	v_mov_b32_e32 v11, 0
	v_mov_b32_e32 v8, 0
	v_mov_b32_e32 v9, 0
	v_mov_b32_e32 v6, 0
	v_mov_b32_e32 v7, 0
	v_mov_b32_e32 v4, 0
	v_mov_b32_e32 v5, 0
	v_add_u32_e32 v202, v12, v121
	v_mov_b64_e32 v[126:127], v[128:129]
	v_mov_b64_e32 v[124:125], v[128:129]
	v_mov_b64_e32 v[122:123], v[128:129]
	v_mov_b64_e32 v[136:137], v[128:129]
	v_mov_b64_e32 v[134:135], v[128:129]
	v_mov_b64_e32 v[132:133], v[128:129]
	v_mov_b64_e32 v[130:131], v[128:129]
	s_waitcnt vmcnt(0)
	v_mov_b64_e32 v[18:19], v[128:129]
	v_mov_b64_e32 v[16:17], v[128:129]
	v_mov_b64_e32 v[14:15], v[128:129]
	v_mov_b64_e32 v[12:13], v[128:129]
	v_mov_b64_e32 v[116:117], v[0:1]
	v_mov_b64_e32 v[112:113], v[0:1]
	v_mov_b64_e32 v[108:109], v[0:1]
	v_mov_b64_e32 v[104:105], v[0:1]
	v_mov_b32_e32 v181, v180
	v_mov_b32_e32 v182, v180
	v_mov_b32_e32 v183, v180
	v_mov_b32_e32 v148, v180
	v_mov_b32_e32 v149, v180
	v_mov_b32_e32 v150, v180
	v_mov_b32_e32 v151, v180
	v_mov_b32_e32 v154, v180
	v_mov_b32_e32 v155, v180
	v_mov_b32_e32 v152, v180
	v_mov_b32_e32 v153, v180
	v_mov_b32_e32 v158, v180
	v_mov_b32_e32 v159, v180
	v_mov_b32_e32 v156, v180
	v_mov_b32_e32 v157, v180
	v_mov_b32_e32 v162, v180
	v_mov_b32_e32 v163, v180
	v_mov_b32_e32 v160, v180
	v_mov_b32_e32 v161, v180
	v_mov_b32_e32 v164, v180
	v_mov_b32_e32 v165, v180
	v_mov_b32_e32 v178, v180
	v_mov_b32_e32 v179, v180
	s_branch .LBB0_348

; #define LAS __attribute__((address_space(3)))
; __device__ __forceinline__ const char* upin(const char* p) { asm volatile("" : "+s"(p)); return p; }
; template <bool GDN, int NT> __device__ __forceinline__ void scan_load(const Frame& F, int b, int h, int dir, const ScanLane& L, int s, ScanOps<NT>& o) {
;     ...
;         const char* base = (const char*)F.PG + (size_t)ud * 32768;
;         const char* bM = upin(base); const char* bB = upin(base + 8192); const char* bQ = upin(base + 16384); const char* bO = upin(base + 24576);
; #pragma unroll
;         for (int ks = 0; ks < 2; ++ks) { o.Mf[ks] = ldun<bf16x8>(bM + ks * 1024, L.o16); o.Qf[ks] = ldun<bf16x8>(bQ + ks * 1024, L.o16); }
; #pragma unroll
;         for (int pr = 0; pr < 2; ++pr) { const v4u qb = ldun<v4u>(bB + pr * 1024, L.o16p), qo = ldun<v4u>(bO + pr * 1024, L.o16p);
;             o.bv[2 * pr] = (v2u){qb.x, qb.y}; o.bv[2 * pr + 1] = (v2u){qb.z, qb.w}; o.ov[2 * pr] = (v2u){qo.x, qo.y}; o.ov[2 * pr + 1] = (v2u){qo.z, qo.w}; }
;         o.wi = (f32x4){1.f, 1.f, 1.f, 1.f};
;     ...
;     const int b = bh >> 2, h = bh & 3;
;     const int lane = fresh_lane(), dir = F.wave >> 2, wq = F.wave & 3, lr = lane & 15, lq = lane >> 4;
;     ScanLane L;
;     L.o16 = (unsigned)((wq * 128 + lq * 16 + lr) * 16); L.o8 = (unsigned)((wq * NT * 64 + lq * 16 + lr) * 8); L.o16p = (unsigned)(wq * NT * 512 + (lq * 16 + lr) * 16); L.zq = (unsigned)(((16 * wq + lr) * ZW + 8 * lq) * 2); L.wi = (unsigned)((16 * wq + 4 * lq) * 4);
;     L.pend = (unsigned)(wq * 2048 + (lq * 16 + lr) * 16);   L.gz = (unsigned)(((16 * wq + 4 * lq) * ZW + 4 * lr) * 2); L.mix = (unsigned)(((16 * wq + 4 * lq) * 1024 + 4 * lr) * 2);
;     LAS bf16_t* St = (LAS bf16_t*)F.lds;
;     f32x4 S[NT];
; #pragma unroll
;     for (int t = 0; t < NT; ++t) S[t] = (f32x4){0.f, 0.f, 0.f, 0.f};
;     float* PEND = F.PEND + (GDN ? (size_t)0 : (size_t)1152 * 4096);
;     ScanOps<NT> A0, A1, A2; ScanFin F0, F1;
;     f32x4 Oprev[4];
; #pragma unroll
;     for (int t = 0; t < 4; ++t) { Oprev[t] = (f32x4){0.f, 0.f, 0.f, 0.f}; F0.pend[t] = (v2u){0u, 0u}; F1.pend[t] = (v2u){0u, 0u}; F0.gz[t] = (v2u){0u, 0u}; F1.gz[t] = (v2u){0u, 0u}; }
;     { const int tl = F.wave * 64 + lane; if (tl < 72) ((LAS float*)(St + 4 * 80 * 72))[tl] = (GDN ? F.GLG : F.GLM)[(b * 4 + h) * 72 + tl]; }
;     scan_load<GDN, NT>(F, b, h, dir, L, 0, A0);
;     scan_load<GDN, NT>(F, b, h, dir, L, 1, A1);
.Lprio_g:
	v_readlane_b32 s0, v251, 38
	v_readlane_b32 s10, v251, 51
	v_and_b32_e32 v3, -16, v0
	v_lshl_add_u32 v192, v0, 4, s0
	v_readlane_b32 s0, v251, 49
	v_readlane_b32 s1, v251, 50
	s_add_u32 s0, s35, s0
	s_addc_u32 s1, s43, s1
	s_add_u32 s4, s0, 0x2000
	s_addc_u32 s5, s1, 0
	s_add_u32 s6, s0, 0x4000
	s_addc_u32 s7, s1, 0
	s_add_u32 s8, s0, 0x6000
	s_addc_u32 s9, s1, 0
	v_readlane_b32 s3, v251, 36
	v_readlane_b32 s11, v251, 52
	s_add_u32 s10, s35, s10
	v_and_b32_e32 v2, 15, v0
	v_add_u32_e32 v4, s3, v3
	s_addc_u32 s11, s43, s11
	v_or_b32_e32 v5, v4, v2
	s_add_u32 s12, s10, 0x2000
	v_lshlrev_b32_e32 v154, 4, v5
	s_addc_u32 s13, s11, 0
	s_add_u32 s14, s10, 0x4000
	global_load_dwordx4 v[42:45], v154, s[0:1] nt
	global_load_dwordx4 v[38:41], v154, s[0:1] offset:1024 nt
	global_load_dwordx4 v[58:61], v154, s[6:7] nt
	global_load_dwordx4 v[50:53], v154, s[6:7] offset:1024 nt
	global_load_dwordx4 v[90:93], v192, s[4:5] nt
	global_load_dwordx4 v[62:65], v192, s[4:5] offset:1024 nt
	global_load_dwordx4 v[82:85], v192, s[8:9] nt
	global_load_dwordx4 v[54:57], v192, s[8:9] offset:1024 nt
	s_addc_u32 s15, s11, 0
	s_add_u32 s18, s10, 0x6000
	s_addc_u32 s19, s11, 0
	global_load_dwordx4 v[70:73], v192, s[12:13] nt
	global_load_dwordx4 v[22:25], v192, s[12:13] offset:1024 nt
	global_load_dwordx4 v[66:69], v192, s[18:19] nt
	global_load_dwordx4 v[18:21], v192, s[18:19] offset:1024 nt
	v_add_u32_e32 v4, s3, v4
	v_ashrrev_i32_e32 v0, 2, v0
	v_or_b32_e32 v4, v4, v2
	v_readlane_b32 s0, v251, 37
	v_and_b32_e32 v0, -4, v0
	v_mov_b32_e32 v155, v1
	v_lshlrev_b32_e32 v193, 3, v4
	v_or_b32_e32 v4, s0, v2
	v_add_u32_e32 v5, s0, v0
	v_lshl_add_u64 v[146:147], s[10:11], 0, v[154:155]
	v_lshl_add_u64 v[148:149], s[14:15], 0, v[154:155]
	s_mov_b64 s[0:1], 0x400
	v_lshl_add_u64 v[150:151], v[146:147], 0, s[0:1]
	v_lshl_add_u64 v[152:153], v[148:149], 0, s[0:1]
	v_readlane_b32 s0, v251, 46
	v_mov_b32_e32 v118, v1
	v_mov_b32_e32 v119, v1
	v_mov_b32_e32 v120, v1
	v_mov_b32_e32 v121, v1
	v_lshlrev_b32_e32 v6, 3, v2
	v_mul_lo_u32 v7, v5, s66
	v_lshl_add_u32 v10, v0, 1, s0
	v_mul_u32_u24_e32 v155, 0x90, v2
	v_readlane_b32 s0, v251, 45
	v_mov_b32_e32 v0, v1
	v_mov_b64_e32 v[114:115], v[118:119]
	v_mov_b64_e32 v[124:125], v[120:121]
	v_mov_b64_e32 v[128:129], v[120:121]
	v_mov_b64_e32 v[144:145], v[120:121]
	v_mov_b64_e32 v[140:141], v[120:121]
	v_mov_b64_e32 v[136:137], v[120:121]
	v_mov_b64_e32 v[132:133], v[120:121]
	v_or_b32_e32 v194, v7, v6
	v_mad_u32_u24 v195, v4, s66, v3
	v_lshlrev_b32_e32 v196, 2, v5
	v_lshl_or_b32 v197, v5, 11, v6
	v_add_u32_e32 v198, s0, v3
	s_waitcnt lgkmcnt(0)
	s_mov_b32 s23, 0
	s_mov_b32 s22, -3
	v_mov_b32_e32 v8, 0
	v_mov_b32_e32 v9, 0
	v_mov_b32_e32 v6, 0
	v_mov_b32_e32 v7, 0
	v_mov_b32_e32 v4, 0
	v_mov_b32_e32 v5, 0
	v_mov_b32_e32 v2, 0
	v_mov_b32_e32 v3, 0
	v_add_u32_e32 v199, v10, v155
	v_mov_b64_e32 v[116:117], v[120:121]
	v_mov_b64_e32 v[122:123], v[118:119]
	v_mov_b64_e32 v[126:127], v[118:119]
	v_mov_b64_e32 v[162:163], v[0:1]
	v_mov_b64_e32 v[160:161], v[0:1]
	v_mov_b64_e32 v[158:159], v[0:1]
	v_mov_b64_e32 v[156:157], v[0:1]
	v_mov_b64_e32 v[182:183], v[0:1]
	v_mov_b64_e32 v[180:181], v[0:1]
	v_mov_b64_e32 v[178:179], v[0:1]
	v_mov_b64_e32 v[164:165], v[0:1]
	v_mov_b64_e32 v[16:17], v[0:1]
	v_mov_b64_e32 v[14:15], v[0:1]
	v_mov_b64_e32 v[12:13], v[0:1]
	v_mov_b64_e32 v[10:11], v[0:1]
	v_mov_b64_e32 v[142:143], v[118:119]
	v_mov_b64_e32 v[138:139], v[118:119]
	v_mov_b64_e32 v[134:135], v[118:119]
	v_mov_b64_e32 v[130:131], v[118:119]
	v_readlane_b32 s24, v251, 53
	v_readlane_b32 s25, v251, 54
	s_branch .LBB0_483

; #define VM_WAIT() asm volatile("s_waitcnt vmcnt(0)" ::: "memory")
;     ...
;     VM_WAIT();
;     __syncthreads();
.LBB0_610:
	s_setprio 0
	s_mov_b64 s[10:11], 0
